# attention tile loop rewritten by hand: software-pipelined QK(t+1)/PV(t) with exp2 and row sums in MFMA gaps, K/V LDS rings offset by one tile, DMA in MFMA shadows
# speedup vs baseline: 1.0175x; 1.0159x over previous
; #define DMA_T(t, s) do { const long go_ = (long)(t) * KVBLK * PITCH; const unsigned sd_ = (unsigned)__builtin_amdgcn_readfirstlane(pdst + (s) * SLOTB); \
;         glds16(ksrc + go_, sd_); glds16(ksrc + go_ + 64, sd_ + OFF_K1); glds16(vsrc + go_, sd_ + OFF_V); glds16(vsrc + go_ + 64, sd_ + OFF_V + 8192); } while (0)
; __device__ __forceinline__ void attn_unit(const int b, const int h, const int qb, const bf16_t* Q, const bf16_t* K, const bf16_t* V, bf16_t* O, ATT_LAS char* shm, const float lam) {
;     const int tid = threadIdx.x, lane = tid & 63, r32 = lane & 31, hi = lane >> 5; const int wid = __builtin_amdgcn_readfirstlane(tid >> 6), sub = wid >> 2, w4 = wid & 3;
;     const long rowbase = (long)b * SEQ; const int q0 = qb * QB2;
;     const bf16_t* Qw = Q + (rowbase + q0 + w4 * QBLK) * PITCH + h * 128 + sub * 64;
;     const bf16_t* Kh = K + rowbase * PITCH + h * 128; const bf16_t* Vh = V + rowbase * PITCH + h * 128;
;     const unsigned lds0 = (unsigned)(uintptr_t)shm;
;     const bf16_t* ksrc = Kh + (long)lane * PITCH + wid * 8;
;     const bf16_t* vsrc = Vh + (long)(16 * (wid & 3) + (lane >> 2)) * PITCH + (wid >> 2) * 32 + (lane & 3) * 8;
;     const unsigned pdst = lds0 + wid * 1024;
;     ...
;     const lds_cptr kp0 = (lds_cptr)shm + sub * OFF_K1 + hi * 1024 + r32 * 16;
;     const lds_cptr vp0 = (lds_cptr)shm + OFF_V + ((lane >> 4) & 1) * 32 + (lane & 3) * 8 + (4 * hi + ((lane & 15) >> 2)) * 64;
;     const int NT = (q0 + QB2) / KVBLK;
;     const int mylast = q0 / KVBLK + (w4 >> 1);
;     DMA_T(0, 0); DMA_T(1, 1);
;     bf16x8 qr[4];
; #pragma unroll
;     for (int d0 = 0; d0 < 4; ++d0) qr[d0] = *reinterpret_cast<const bf16x8*>(&Qw[(long)r32 * PITCH + d0 * 16 + hi * 8]);
;     asm volatile("" : "+v"(qr[0]), "+v"(qr[1]), "+v"(qr[2]), "+v"(qr[3]));
;     f32x16 o[4]; o[0] = f32x16{}; o[1] = f32x16{}; o[2] = f32x16{}; o[3] = f32x16{};
;     float l_reg = 0.f;
;     int slot = 0, slot2 = 2;
.LBB0_466:
	s_bitcmp0_b32 s34, 0
	v_readfirstlane_b32 s3, v164
	s_cselect_b32 s44, s6, s7
	s_bfe_u32 s31, s3, 0x20006
	s_lshl_b32 s30, s31, 14
	s_lshl_b32 s16, s44, 16
	s_or_b32 s16, s30, s16
	s_or_b32 s26, s0, s16
	s_mov_b32 s27, s1
	s_lshr_b32 s45, s3, 6
	s_lshr_b32 s39, s3, 8
	s_lshl_b32 s46, s44, 7
	s_lshl_b64 s[26:27], s[26:27], 1
	s_add_u32 s36, s85, s26
	s_addc_u32 s37, s86, s27
	s_lshl_b32 s35, s34, 7
	s_lshl_b32 s16, s34, 8
	s_add_u32 s38, s36, s16
	s_addc_u32 s41, s37, 0
	s_lshl_b32 s36, s39, 6
	s_lshl_b32 s40, s39, 7
	s_add_u32 s40, s38, s40
	s_addc_u32 s41, s41, 0
	s_add_u32 s42, s8, s16
	s_addc_u32 s43, s9, 0
	s_lshl_b32 s38, s31, 13
	v_or_b32_e32 v0, s38, v152
	v_lshl_add_u64 v[2:3], v[114:115], 0, s[16:17]
	s_lshl_b32 s16, s45, 4
	v_lshlrev_b32_e32 v0, 1, v0
	s_lshl_b32 s31, s45, 10
	s_mov_b32 s37, s17
	v_lshl_add_u64 v[2:3], v[2:3], 0, s[16:17]
	v_lshl_add_u64 v[4:5], s[42:43], 0, v[0:1]
	s_add_i32 s31, s31, 0
	s_mov_b32 s16, m0
	s_mov_b32 m0, s31
	s_nop 0
	global_load_lds_dwordx4 v[2:3], off
	s_mov_b32 m0, s16
	v_lshl_add_u64 v[4:5], v[4:5], 0, s[36:37]
	v_mov_b32_e32 v121, v1
	v_lshl_add_u64 v[6:7], v[2:3], 0, s[18:19]
	s_add_i32 s16, s31, 0x2000
	s_mov_b32 s42, m0
	s_mov_b32 m0, s16
	s_nop 0
	global_load_lds_dwordx4 v[6:7], off
	s_mov_b32 m0, s42
	v_lshl_add_u64 v[4:5], v[4:5], 0, v[120:121]
	s_add_i32 s16, s31, 0x4000
	s_mov_b32 s42, m0
	s_mov_b32 m0, s16
	s_nop 0
	global_load_lds_dwordx4 v[4:5], off
	s_mov_b32 m0, s42
	v_lshl_add_u64 v[6:7], v[4:5], 0, s[18:19]
	s_add_i32 s16, s31, 0x6000
	s_mov_b32 s42, m0
	s_mov_b32 m0, s16
	s_nop 0
	global_load_lds_dwordx4 v[6:7], off
	s_mov_b32 m0, s42
	s_add_i32 s16, s31, 0x8000
	v_lshl_add_u64 v[6:7], v[2:3], 0, s[20:21]
	s_mov_b32 s42, m0
	s_mov_b32 m0, s16
	s_nop 0
	global_load_lds_dwordx4 v[6:7], off
	s_mov_b32 m0, s42
	v_lshl_add_u64 v[2:3], v[2:3], 0, s[22:23]
	s_add_i32 s16, s31, 0xa000
	s_mov_b32 s42, m0
	s_mov_b32 m0, s16
	s_nop 0
	global_load_lds_dwordx4 v[2:3], off
	s_mov_b32 m0, s42
	v_lshl_add_u64 v[2:3], v[4:5], 0, s[20:21]
	s_add_i32 s16, s31, 0xc000
	s_mov_b32 s42, m0
	s_mov_b32 m0, s16
	s_nop 0
	global_load_lds_dwordx4 v[2:3], off
	s_mov_b32 m0, s42
	v_lshl_add_u64 v[2:3], v[4:5], 0, s[22:23]
	s_add_i32 s16, s31, 0xe000
	s_mov_b32 s42, m0
	s_mov_b32 m0, s16
	s_nop 0
	global_load_lds_dwordx4 v[2:3], off
	s_mov_b32 m0, s42
	global_load_dwordx4 v[98:101], v213, s[40:41] offset:96
	global_load_dwordx4 v[102:105], v213, s[40:41] offset:64
	global_load_dwordx4 v[106:109], v213, s[40:41] offset:32
	global_load_dwordx4 v[110:113], v213, s[40:41]
	v_mov_b32_e32 v14, v1
	v_mov_b32_e32 v15, v1
	v_mov_b32_e32 v2, v1
	v_mov_b32_e32 v3, v1
	v_mov_b32_e32 v4, v1
	v_mov_b32_e32 v5, v1
	v_mov_b32_e32 v6, v1
	v_mov_b32_e32 v7, v1
	v_mov_b32_e32 v8, v1
	v_mov_b32_e32 v9, v1
	v_mov_b32_e32 v10, v1
	v_mov_b32_e32 v11, v1
	v_mov_b32_e32 v12, v1
	v_mov_b32_e32 v13, v1
	s_addk_i32 s46, 0x80
	s_bfe_u32 s16, s45, 0x10001
	s_lshl_b32 s42, s44, 1
	s_lshr_b32 s44, s3, 2
	v_lshl_add_u64 v[16:17], s[36:37], 0, v[0:1]
	v_mov_b32_e32 v0, v1
	v_mov_b64_e32 v[64:65], v[14:15]
	v_mov_b64_e32 v[48:49], v[14:15]
	v_mov_b64_e32 v[32:33], v[14:15]
	s_lshr_b32 s43, s46, 6
	s_or_b32 s42, s16, s42
	s_and_b32 s16, s44, 0x3ffffff0
	v_lshl_add_u64 v[142:143], v[118:119], 0, v[16:17]
	v_mov_b64_e32 v[62:63], v[12:13]
	v_mov_b64_e32 v[60:61], v[10:11]
	v_mov_b64_e32 v[58:59], v[8:9]
	v_mov_b64_e32 v[56:57], v[6:7]
	v_mov_b64_e32 v[54:55], v[4:5]
	v_mov_b64_e32 v[52:53], v[2:3]
	v_mov_b64_e32 v[50:51], v[0:1]
	v_mov_b64_e32 v[46:47], v[12:13]
	v_mov_b64_e32 v[44:45], v[10:11]
	v_mov_b64_e32 v[42:43], v[8:9]
	v_mov_b64_e32 v[40:41], v[6:7]
	v_mov_b64_e32 v[38:39], v[4:5]
	v_mov_b64_e32 v[36:37], v[2:3]
	v_mov_b64_e32 v[34:35], v[0:1]
	v_mov_b64_e32 v[30:31], v[12:13]
	v_mov_b64_e32 v[28:29], v[10:11]
	v_mov_b64_e32 v[26:27], v[8:9]
	v_mov_b64_e32 v[24:25], v[6:7]
	v_mov_b64_e32 v[22:23], v[4:5]
	v_mov_b64_e32 v[20:21], v[2:3]
	v_mov_b64_e32 v[18:19], v[0:1]
	v_mov_b64_e32 v[16:17], v[14:15]
	v_mov_b32_e32 v121, 0
	s_mov_b32 s40, 0
	s_mov_b32 s41, 2
	v_lshl_add_u32 v123, s39, 13, v154
	s_add_i32 s44, s43, -2
	s_add_i32 s45, s43, -1
	v_lshl_add_u64 v[140:141], v[116:117], 0, s[16:17]
	v_mov_b64_e32 v[14:15], v[12:13]
	v_mov_b64_e32 v[12:13], v[10:11]
	v_mov_b64_e32 v[10:11], v[8:9]
	v_mov_b64_e32 v[8:9], v[6:7]
	v_mov_b64_e32 v[6:7], v[4:5]
	v_mov_b64_e32 v[4:5], v[2:3]
	v_mov_b64_e32 v[2:3], v[0:1]
	s_mov_b32 s16, 0
	s_waitcnt vmcnt(0)
	s_cmp_lt_u32 s43, 3
	s_cbranch_scc1 .Latt_nok2
	s_add_i32 s46, s31, 0x10000
	s_mov_b32 m0, s46
	v_lshl_add_u64 v[162:163], v[140:141], 0, s[18:19]
	global_load_lds_dwordx4 v[140:141], off
	s_add_i32 m0, s46, 0x2000
	s_nop 0
	global_load_lds_dwordx4 v[162:163], off
	v_lshl_add_u64 v[140:141], v[140:141], 0, s[20:21]
; #define ATT_LAS __attribute__((address_space(3)))
; __device__ __forceinline__ unsigned cvtpk_s(float lo, float hi) { f32x2_t v = {lo, hi}; bf16x2_t b = __builtin_convertvector(v, bf16x2_t); return __builtin_bit_cast(unsigned, b); }
; #define ATT_WAIT_BAR(N) asm volatile("s_waitcnt vmcnt(" #N ") lgkmcnt(0)\n\ts_barrier" ::: "memory")
; #define DMA_T(t, s) do { const long go_ = (long)(t) * KVBLK * PITCH; const unsigned sd_ = (unsigned)__builtin_amdgcn_readfirstlane(pdst + (s) * SLOTB); \
;         glds16(ksrc + go_, sd_); glds16(ksrc + go_ + 64, sd_ + OFF_K1); glds16(vsrc + go_, sd_ + OFF_V); glds16(vsrc + go_ + 64, sd_ + OFF_V + 8192); } while (0)
; __device__ __forceinline__ void attn_unit(const int b, const int h, const int qb, const bf16_t* Q, const bf16_t* K, const bf16_t* V, bf16_t* O, ATT_LAS char* shm, const float lam) {
;     ...
;     for (int t = 0; t < NT; ++t) {
;         if (t + 1 < NT) { ATT_WAIT_BAR(4); } else { ATT_WAIT_BAR(0); }
;         if (t + 2 < NT) DMA_T(t + 2, slot2);
;         if (t <= mylast) {
;             const lds_cptr kp = kp0 + slot * SLOTB; const lds_cptr vp = vp0 + slot * SLOTB;
;     ...
;             bf16x8 kf[8]; s16x4 va[8], vb[8];
; #pragma unroll
;             for (int d0 = 0; d0 < 4; ++d0) { kf[2 * d0] = *(const ATT_LAS bf16x8*)(kp + d0 * 2048); kf[2 * d0 + 1] = *(const ATT_LAS bf16x8*)(kp + d0 * 2048 + 512); }
;             ATT_VLOAD(va, 0);
;             ATT_SBAR();
;             f32x16 p0 = f32x16{}, p1 = f32x16{};
; #pragma unroll
;             for (int d0 = 0; d0 < 4; ++d0) { p0 = __builtin_amdgcn_mfma_f32_32x32x16_bf16(kf[2 * d0], qr[d0], p0, 0, 0, 0); p1 = __builtin_amdgcn_mfma_f32_32x32x16_bf16(kf[2 * d0 + 1], qr[d0], p1, 0, 0, 0); }
;             ATT_SBAR();
;             ATT_VLOAD(vb, 1);
;             ATT_SBAR();
; #pragma unroll
;             for (int r = 0; r < 16; ++r) { p0[r] = __builtin_amdgcn_exp2f(p0[r]); p1[r] = __builtin_amdgcn_exp2f(p1[r]); }
;             u32x4 pw[4];
; #pragma unroll
;             for (int j = 0; j < 4; ++j) { pw[0][j] = cvtpk_s(p0[2 * j], p0[2 * j + 1]); pw[1][j] = cvtpk_s(p0[8 + 2 * j], p0[9 + 2 * j]); pw[2][j] = cvtpk_s(p1[2 * j], p1[2 * j + 1]); pw[3][j] = cvtpk_s(p1[8 + 2 * j], p1[9 + 2 * j]); }
;             { float sa = 0.f, sb = 0.f;
; #pragma unroll
;               for (int r = 0; r < 16; ++r) { sa += p0[r]; sb += p1[r]; }
;               l_reg += sa + sb; }
.Latt_nok2:
	s_and_b32 s98, s42, 1
	s_barrier
	v_add_u32_e32 v0, 0, v123
	ds_read_b128 v[232:235], v0 offset:0
	ds_read_b128 v[236:239], v0 offset:2048
	ds_read_b128 v[240:243], v0 offset:4096
	ds_read_b128 v[244:247], v0 offset:6144
	s_waitcnt lgkmcnt(3)
	v_mfma_f32_32x32x16_bf16 v[66:81], v[232:235], v[110:113], 0
	ds_read_b128 v[232:235], v0 offset:512
	s_waitcnt lgkmcnt(3)
	v_mfma_f32_32x32x16_bf16 v[66:81], v[236:239], v[106:109], v[66:81]
	ds_read_b128 v[236:239], v0 offset:2560
	s_waitcnt lgkmcnt(3)
	v_mfma_f32_32x32x16_bf16 v[66:81], v[240:243], v[102:105], v[66:81]
	ds_read_b128 v[240:243], v0 offset:4608
	s_waitcnt lgkmcnt(3)
	v_mfma_f32_32x32x16_bf16 v[66:81], v[244:247], v[98:101], v[66:81]
	ds_read_b128 v[244:247], v0 offset:6656
	s_waitcnt lgkmcnt(3)
	v_mfma_f32_32x32x16_bf16 v[82:97], v[232:235], v[110:113], 0
	s_waitcnt lgkmcnt(2)
	v_mfma_f32_32x32x16_bf16 v[82:97], v[236:239], v[106:109], v[82:97]
	s_waitcnt lgkmcnt(1)
	v_mfma_f32_32x32x16_bf16 v[82:97], v[240:243], v[102:105], v[82:97]
	s_waitcnt lgkmcnt(0)
	v_mfma_f32_32x32x16_bf16 v[82:97], v[244:247], v[98:101], v[82:97]
	s_nop 15
	v_exp_f32_e32 v66, v66
	v_exp_f32_e32 v67, v67
	v_exp_f32_e32 v68, v68
	v_exp_f32_e32 v69, v69
	v_exp_f32_e32 v70, v70
	v_exp_f32_e32 v71, v71
	v_exp_f32_e32 v72, v72
	v_exp_f32_e32 v73, v73
	v_exp_f32_e32 v74, v74
	v_exp_f32_e32 v75, v75
	v_exp_f32_e32 v76, v76
	v_exp_f32_e32 v77, v77
	v_exp_f32_e32 v78, v78
	v_exp_f32_e32 v79, v79
	v_exp_f32_e32 v80, v80
	v_exp_f32_e32 v81, v81
	v_exp_f32_e32 v82, v82
	v_exp_f32_e32 v83, v83
	v_exp_f32_e32 v84, v84
	v_exp_f32_e32 v85, v85
	v_exp_f32_e32 v86, v86
	v_exp_f32_e32 v87, v87
	v_exp_f32_e32 v88, v88
	v_exp_f32_e32 v89, v89
	v_exp_f32_e32 v90, v90
	v_exp_f32_e32 v91, v91
	v_exp_f32_e32 v92, v92
	v_exp_f32_e32 v93, v93
	v_exp_f32_e32 v94, v94
	v_exp_f32_e32 v95, v95
	v_exp_f32_e32 v96, v96
	v_exp_f32_e32 v97, v97
	v_add_f32_e32 v252, v66, v67
	v_add_f32_e32 v252, v252, v68
	v_add_f32_e32 v252, v252, v69
	v_add_f32_e32 v252, v252, v70
	v_add_f32_e32 v252, v252, v71
	v_add_f32_e32 v252, v252, v72
	v_add_f32_e32 v252, v252, v73
	v_add_f32_e32 v252, v252, v74
	v_add_f32_e32 v252, v252, v75
	v_add_f32_e32 v252, v252, v76
	v_add_f32_e32 v252, v252, v77
	v_add_f32_e32 v252, v252, v78
	v_add_f32_e32 v252, v252, v79
	v_add_f32_e32 v252, v252, v80
	v_add_f32_e32 v252, v252, v81
	v_add_f32_e32 v253, v82, v83
	v_add_f32_e32 v253, v253, v84
	v_add_f32_e32 v253, v253, v85
	v_add_f32_e32 v253, v253, v86
	v_add_f32_e32 v253, v253, v87
	v_add_f32_e32 v253, v253, v88
	v_add_f32_e32 v253, v253, v89
	v_add_f32_e32 v253, v253, v90
	v_add_f32_e32 v253, v253, v91
	v_add_f32_e32 v253, v253, v92
	v_add_f32_e32 v253, v253, v93
	v_add_f32_e32 v253, v253, v94
	v_add_f32_e32 v253, v253, v95
	v_add_f32_e32 v253, v253, v96
	v_add_f32_e32 v253, v253, v97
	s_cmp_lt_u32 s43, 3
	s_cbranch_scc1 .Latt_tail
.Latt_top:
	s_add_i32 s36, s16, 3
	s_cmp_lt_u32 s36, s43
	s_cselect_b32 s99, 1, 0
	s_waitcnt vmcnt(4)
	s_barrier
	s_add_i32 s36, s40, 1
	s_cmp_lg_u32 s40, 2
	s_cselect_b32 s36, s36, 0
	s_lshl_b32 s36, s36, 15
	v_add_u32_e32 v0, s36, v123
	s_lshl_b32 s37, s40, 15
	v_add_u32_e32 v125, s37, v156
	s_add_i32 s46, s37, s31
	s_lshl_b32 s37, s41, 15
	s_add_i32 s37, s37, s31
	s_addk_i32 s37, 0x4000
	ds_read_b128 v[232:235], v0 offset:0
	ds_read_b128 v[236:239], v0 offset:2048
	ds_read_b128 v[240:243], v0 offset:4096
	ds_read_b128 v[244:247], v0 offset:6144
	ds_read_b64_tr_b16 v[248:249], v125 offset:16384
	ds_read_b64_tr_b16 v[250:251], v125 offset:16896
	ds_read_b64_tr_b16 v[158:159], v125 offset:17408
	ds_read_b64_tr_b16 v[160:161], v125 offset:17920
	ds_read_b64_tr_b16 v[166:167], v125 offset:18432
	ds_read_b64_tr_b16 v[168:169], v125 offset:18944
	v_cvt_pk_bf16_f32 v216, v66, v67
	v_cvt_pk_bf16_f32 v217, v68, v69
	v_cvt_pk_bf16_f32 v218, v70, v71
	v_cvt_pk_bf16_f32 v219, v72, v73
	v_cvt_pk_bf16_f32 v220, v74, v75
	v_cvt_pk_bf16_f32 v221, v76, v77
	v_cvt_pk_bf16_f32 v222, v78, v79
	v_cvt_pk_bf16_f32 v223, v80, v81
	v_add_f32_e32 v121, v121, v252
	v_add_f32_e32 v121, v121, v253
	s_waitcnt lgkmcnt(9)
	v_mfma_f32_32x32x16_bf16 v[66:81], v[232:235], v[110:113], 0
	ds_read_b128 v[232:235], v0 offset:512
	v_cvt_pk_bf16_f32 v224, v82, v83
	v_cvt_pk_bf16_f32 v225, v84, v85
	v_cvt_pk_bf16_f32 v226, v86, v87
	v_cvt_pk_bf16_f32 v227, v88, v89
	s_waitcnt lgkmcnt(9)
	v_mfma_f32_32x32x16_bf16 v[66:81], v[236:239], v[106:109], v[66:81]
	ds_read_b128 v[236:239], v0 offset:2560
	v_cvt_pk_bf16_f32 v228, v90, v91
	v_cvt_pk_bf16_f32 v229, v92, v93
	v_cvt_pk_bf16_f32 v230, v94, v95
	v_cvt_pk_bf16_f32 v231, v96, v97
	s_waitcnt lgkmcnt(9)
	v_mfma_f32_32x32x16_bf16 v[66:81], v[240:243], v[102:105], v[66:81]
	ds_read_b128 v[240:243], v0 offset:4608
	s_cmp_lg_u32 s99, 0
	s_cbranch_scc0 .Latt_m_nok
	s_mov_b32 m0, s46
	v_lshl_add_u64 v[162:163], v[140:141], 0, s[18:19]
	global_load_lds_dwordx4 v[140:141], off
	s_add_i32 m0, s46, 0x2000
	s_nop 0
	global_load_lds_dwordx4 v[162:163], off
; __device__ __forceinline__ unsigned cvtpk_s(float lo, float hi) { f32x2_t v = {lo, hi}; bf16x2_t b = __builtin_convertvector(v, bf16x2_t); return __builtin_bit_cast(unsigned, b); }
; #define ATT_SBAR() __builtin_amdgcn_sched_barrier(0)
; #define ATT_VLOAD(dst, d0) do { _Pragma("unroll") for (int ks = 0; ks < 4; ++ks) { dst[2 * ks] = vtr(vp + (d0) * 4096 + ks * 1024); dst[2 * ks + 1] = vtr(vp + (d0) * 4096 + ks * 1024 + 512); } } while (0)
; #define ATT_PV(acc, src) do { _Pragma("unroll") for (int ks = 0; ks < 4; ++ks) { const bf16x8 vf_ = (bf16x8){src[2 * ks][0], src[2 * ks][1], src[2 * ks][2], src[2 * ks][3], src[2 * ks + 1][0], src[2 * ks + 1][1], src[2 * ks + 1][2], src[2 * ks + 1][3]}; \
;                 acc = __builtin_amdgcn_mfma_f32_32x32x16_bf16(__builtin_bit_cast(bf16x8, pw[ks]), vf_, acc, 0, 0, 0); } } while (0)
; __device__ __forceinline__ void attn_unit(const int b, const int h, const int qb, const bf16_t* Q, const bf16_t* K, const bf16_t* V, bf16_t* O, ATT_LAS char* shm, const float lam) {
;     ...
;             for (int r = 0; r < 16; ++r) { p0[r] = __builtin_amdgcn_exp2f(p0[r]); p1[r] = __builtin_amdgcn_exp2f(p1[r]); }
;             u32x4 pw[4];
; #pragma unroll
;             for (int j = 0; j < 4; ++j) { pw[0][j] = cvtpk_s(p0[2 * j], p0[2 * j + 1]); pw[1][j] = cvtpk_s(p0[8 + 2 * j], p0[9 + 2 * j]); pw[2][j] = cvtpk_s(p1[2 * j], p1[2 * j + 1]); pw[3][j] = cvtpk_s(p1[8 + 2 * j], p1[9 + 2 * j]); }
;             { float sa = 0.f, sb = 0.f;
; #pragma unroll
;               for (int r = 0; r < 16; ++r) { sa += p0[r]; sb += p1[r]; }
;               l_reg += sa + sb; }
;             ATT_PV(o[0], va);
;             ATT_SBAR();
;             ATT_VLOAD(va, 2);
;             ATT_SBAR();
;             ATT_PV(o[1], vb);
;             ATT_SBAR();
;             ATT_VLOAD(vb, 3);
;             ATT_SBAR();
;             ATT_PV(o[2], va);
;             ATT_SBAR();
;             ATT_PV(o[3], vb);
;     ...
;         }
;         slot = (slot == NSLOT - 1) ? 0 : slot + 1; slot2 = (slot2 == NSLOT - 1) ? 0 : slot2 + 1;
.Latt_m_nok:
	s_waitcnt lgkmcnt(9)
	v_mfma_f32_32x32x16_bf16 v[66:81], v[244:247], v[98:101], v[66:81]
	ds_read_b128 v[244:247], v0 offset:6656
	s_waitcnt lgkmcnt(3)
	v_mfma_f32_32x32x16_bf16 v[82:97], v[232:235], v[110:113], 0
	ds_read_b64_tr_b16 v[232:233], v125 offset:19456
	ds_read_b64_tr_b16 v[234:235], v125 offset:19968
	s_mov_b32 m0, s37
	v_lshl_add_u64 v[162:163], v[142:143], 0, s[18:19]
	global_load_lds_dwordx4 v[142:143], off
	s_waitcnt lgkmcnt(4)
	v_mfma_f32_32x32x16_bf16 v[82:97], v[236:239], v[106:109], v[82:97]
	ds_read_b64_tr_b16 v[236:237], v125 offset:20480
	ds_read_b64_tr_b16 v[238:239], v125 offset:20992
	s_add_i32 m0, s37, 0x2000
	s_nop 0
	global_load_lds_dwordx4 v[162:163], off
	s_waitcnt lgkmcnt(5)
	v_mfma_f32_32x32x16_bf16 v[82:97], v[240:243], v[102:105], v[82:97]
	ds_read_b64_tr_b16 v[240:241], v125 offset:21504
	ds_read_b64_tr_b16 v[242:243], v125 offset:22016
	s_waitcnt lgkmcnt(6)
	v_mfma_f32_32x32x16_bf16 v[82:97], v[244:247], v[98:101], v[82:97]
	ds_read_b64_tr_b16 v[244:245], v125 offset:22528
	ds_read_b64_tr_b16 v[246:247], v125 offset:23040
	v_mfma_f32_32x32x16_bf16 v[50:65], v[216:219], v[248:251], v[50:65]
	ds_read_b64_tr_b16 v[248:249], v125 offset:23552
	ds_read_b64_tr_b16 v[250:251], v125 offset:24064
	v_exp_f32_e32 v66, v66
	v_exp_f32_e32 v67, v67
	v_mfma_f32_32x32x16_bf16 v[50:65], v[220:223], v[158:161], v[50:65]
	ds_read_b64_tr_b16 v[158:159], v125 offset:24576
	ds_read_b64_tr_b16 v[160:161], v125 offset:25088
	v_add_f32_e32 v252, v66, v67
	v_exp_f32_e32 v68, v68
	v_exp_f32_e32 v69, v69
	v_mfma_f32_32x32x16_bf16 v[50:65], v[224:227], v[166:169], v[50:65]
	ds_read_b64_tr_b16 v[166:167], v125 offset:25600
	ds_read_b64_tr_b16 v[168:169], v125 offset:26112
	v_add_f32_e32 v252, v252, v68
	v_add_f32_e32 v252, v252, v69
	v_exp_f32_e32 v70, v70
	v_exp_f32_e32 v71, v71
	s_waitcnt lgkmcnt(12)
	v_mfma_f32_32x32x16_bf16 v[50:65], v[228:231], v[232:235], v[50:65]
	ds_read_b64_tr_b16 v[232:233], v125 offset:26624
	ds_read_b64_tr_b16 v[234:235], v125 offset:27136
	v_add_f32_e32 v252, v252, v70
	v_add_f32_e32 v252, v252, v71
	v_exp_f32_e32 v72, v72
	v_exp_f32_e32 v73, v73
	s_waitcnt lgkmcnt(12)
	v_mfma_f32_32x32x16_bf16 v[34:49], v[216:219], v[236:239], v[34:49]
	ds_read_b64_tr_b16 v[236:237], v125 offset:27648
	ds_read_b64_tr_b16 v[238:239], v125 offset:28160
	v_add_f32_e32 v252, v252, v72
	v_add_f32_e32 v252, v252, v73
	v_exp_f32_e32 v74, v74
	v_exp_f32_e32 v75, v75
	s_waitcnt lgkmcnt(12)
	v_mfma_f32_32x32x16_bf16 v[34:49], v[220:223], v[240:243], v[34:49]
	ds_read_b64_tr_b16 v[240:241], v125 offset:28672
	ds_read_b64_tr_b16 v[242:243], v125 offset:29184
	v_add_f32_e32 v252, v252, v74
	v_add_f32_e32 v252, v252, v75
	v_exp_f32_e32 v76, v76
	v_exp_f32_e32 v77, v77
	s_waitcnt lgkmcnt(12)
	v_mfma_f32_32x32x16_bf16 v[34:49], v[224:227], v[244:247], v[34:49]
	ds_read_b64_tr_b16 v[244:245], v125 offset:29696
	ds_read_b64_tr_b16 v[246:247], v125 offset:30208
	v_add_f32_e32 v252, v252, v76
	v_add_f32_e32 v252, v252, v77
	v_exp_f32_e32 v78, v78
	v_exp_f32_e32 v79, v79
	s_waitcnt lgkmcnt(12)
	v_mfma_f32_32x32x16_bf16 v[34:49], v[228:231], v[248:251], v[34:49]
	ds_read_b64_tr_b16 v[248:249], v125 offset:30720
	ds_read_b64_tr_b16 v[250:251], v125 offset:31232
	v_add_f32_e32 v252, v252, v78
	v_add_f32_e32 v252, v252, v79
	v_exp_f32_e32 v80, v80
	v_exp_f32_e32 v81, v81
	s_waitcnt lgkmcnt(12)
	v_mfma_f32_32x32x16_bf16 v[18:33], v[216:219], v[158:161], v[18:33]
	ds_read_b64_tr_b16 v[158:159], v125 offset:31744
	ds_read_b64_tr_b16 v[160:161], v125 offset:32256
	v_add_f32_e32 v252, v252, v80
	v_add_f32_e32 v252, v252, v81
	v_exp_f32_e32 v82, v82
	v_exp_f32_e32 v83, v83
	s_waitcnt lgkmcnt(12)
	v_mfma_f32_32x32x16_bf16 v[18:33], v[220:223], v[166:169], v[18:33]
	v_add_f32_e32 v253, v82, v83
	v_exp_f32_e32 v84, v84
	v_exp_f32_e32 v85, v85
	s_waitcnt lgkmcnt(10)
	v_mfma_f32_32x32x16_bf16 v[18:33], v[224:227], v[232:235], v[18:33]
	v_add_f32_e32 v253, v253, v84
	v_add_f32_e32 v253, v253, v85
	v_exp_f32_e32 v86, v86
	v_exp_f32_e32 v87, v87
	s_waitcnt lgkmcnt(8)
	v_mfma_f32_32x32x16_bf16 v[18:33], v[228:231], v[236:239], v[18:33]
	v_add_f32_e32 v253, v253, v86
	v_add_f32_e32 v253, v253, v87
	v_exp_f32_e32 v88, v88
	v_exp_f32_e32 v89, v89
	s_waitcnt lgkmcnt(6)
	v_mfma_f32_32x32x16_bf16 v[2:17], v[216:219], v[240:243], v[2:17]
	v_add_f32_e32 v253, v253, v88
	v_add_f32_e32 v253, v253, v89
	v_exp_f32_e32 v90, v90
	v_exp_f32_e32 v91, v91
	s_waitcnt lgkmcnt(4)
	v_mfma_f32_32x32x16_bf16 v[2:17], v[220:223], v[244:247], v[2:17]
	v_add_f32_e32 v253, v253, v90
	v_add_f32_e32 v253, v253, v91
	v_exp_f32_e32 v92, v92
	v_exp_f32_e32 v93, v93
	s_waitcnt lgkmcnt(2)
	v_mfma_f32_32x32x16_bf16 v[2:17], v[224:227], v[248:251], v[2:17]
	v_add_f32_e32 v253, v253, v92
	v_add_f32_e32 v253, v253, v93
	v_exp_f32_e32 v94, v94
	v_exp_f32_e32 v95, v95
	s_waitcnt lgkmcnt(0)
	v_mfma_f32_32x32x16_bf16 v[2:17], v[228:231], v[158:161], v[2:17]
	v_add_f32_e32 v253, v253, v94
	v_add_f32_e32 v253, v253, v95
	v_exp_f32_e32 v96, v96
	v_exp_f32_e32 v97, v97
	v_add_f32_e32 v253, v253, v96
	v_add_f32_e32 v253, v253, v97
	s_add_i32 s16, s16, 1
	s_add_i32 s36, s40, 1
	s_cmp_lg_u32 s40, 2
	s_cselect_b32 s40, s36, 0
	s_add_i32 s36, s41, 1
	s_cmp_lg_u32 s41, 2
	s_cselect_b32 s41, s36, 0
	v_lshl_add_u64 v[140:141], v[140:141], 0, s[20:21]
	v_lshl_add_u64 v[142:143], v[142:143], 0, s[20:21]
	s_cmp_lt_u32 s16, s44
	s_cbranch_scc1 .Latt_top
; #define ATT_LAS __attribute__((address_space(3)))
; __device__ __forceinline__ unsigned cvtpk_s(float lo, float hi) { f32x2_t v = {lo, hi}; bf16x2_t b = __builtin_convertvector(v, bf16x2_t); return __builtin_bit_cast(unsigned, b); }
; #define ATT_WAIT_BAR(N) asm volatile("s_waitcnt vmcnt(" #N ") lgkmcnt(0)\n\ts_barrier" ::: "memory")
; __device__ __forceinline__ void attn_unit(const int b, const int h, const int qb, const bf16_t* Q, const bf16_t* K, const bf16_t* V, bf16_t* O, ATT_LAS char* shm, const float lam) {
;     ...
;     for (int t = 0; t < NT; ++t) {
;         if (t + 1 < NT) { ATT_WAIT_BAR(4); } else { ATT_WAIT_BAR(0); }
;         if (t + 2 < NT) DMA_T(t + 2, slot2);
;         if (t <= mylast) {
;             const lds_cptr kp = kp0 + slot * SLOTB; const lds_cptr vp = vp0 + slot * SLOTB;
;     ...
;             bf16x8 kf[8]; s16x4 va[8], vb[8];
; #pragma unroll
;             for (int d0 = 0; d0 < 4; ++d0) { kf[2 * d0] = *(const ATT_LAS bf16x8*)(kp + d0 * 2048); kf[2 * d0 + 1] = *(const ATT_LAS bf16x8*)(kp + d0 * 2048 + 512); }
;             ATT_VLOAD(va, 0);
;             ATT_SBAR();
;             f32x16 p0 = f32x16{}, p1 = f32x16{};
; #pragma unroll
;             for (int d0 = 0; d0 < 4; ++d0) { p0 = __builtin_amdgcn_mfma_f32_32x32x16_bf16(kf[2 * d0], qr[d0], p0, 0, 0, 0); p1 = __builtin_amdgcn_mfma_f32_32x32x16_bf16(kf[2 * d0 + 1], qr[d0], p1, 0, 0, 0); }
;             ATT_SBAR();
;             ATT_VLOAD(vb, 1);
;             ATT_SBAR();
; #pragma unroll
;             for (int r = 0; r < 16; ++r) { p0[r] = __builtin_amdgcn_exp2f(p0[r]); p1[r] = __builtin_amdgcn_exp2f(p1[r]); }
;             u32x4 pw[4];
; #pragma unroll
;             for (int j = 0; j < 4; ++j) { pw[0][j] = cvtpk_s(p0[2 * j], p0[2 * j + 1]); pw[1][j] = cvtpk_s(p0[8 + 2 * j], p0[9 + 2 * j]); pw[2][j] = cvtpk_s(p1[2 * j], p1[2 * j + 1]); pw[3][j] = cvtpk_s(p1[8 + 2 * j], p1[9 + 2 * j]); }
;             { float sa = 0.f, sb = 0.f;
; #pragma unroll
;               for (int r = 0; r < 16; ++r) { sa += p0[r]; sb += p1[r]; }
;               l_reg += sa + sb; }
;             ATT_PV(o[0], va);
;             ATT_SBAR();
;             ATT_VLOAD(va, 2);
;             ATT_SBAR();
;             ATT_PV(o[1], vb);
;             ATT_SBAR();
;             ATT_VLOAD(vb, 3);
;             ATT_SBAR();
;             ATT_PV(o[2], va);
;             ATT_SBAR();
;             ATT_PV(o[3], vb);
.Latt_tail:
	s_waitcnt vmcnt(2)
	s_barrier
	s_cmp_lg_u32 s98, 0
	s_cbranch_scc0 .Latt_low
	s_add_i32 s36, s40, 1
	s_cmp_lg_u32 s40, 2
	s_cselect_b32 s36, s36, 0
	s_lshl_b32 s36, s36, 15
	v_add_u32_e32 v0, s36, v123
	s_lshl_b32 s37, s40, 15
	v_add_u32_e32 v125, s37, v156
	ds_read_b128 v[232:235], v0 offset:0
	ds_read_b128 v[236:239], v0 offset:2048
	ds_read_b128 v[240:243], v0 offset:4096
	ds_read_b128 v[244:247], v0 offset:6144
	ds_read_b64_tr_b16 v[248:249], v125 offset:16384
	ds_read_b64_tr_b16 v[250:251], v125 offset:16896
	ds_read_b64_tr_b16 v[158:159], v125 offset:17408
	ds_read_b64_tr_b16 v[160:161], v125 offset:17920
	ds_read_b64_tr_b16 v[166:167], v125 offset:18432
	ds_read_b64_tr_b16 v[168:169], v125 offset:18944
	v_cvt_pk_bf16_f32 v216, v66, v67
	v_cvt_pk_bf16_f32 v217, v68, v69
	v_cvt_pk_bf16_f32 v218, v70, v71
	v_cvt_pk_bf16_f32 v219, v72, v73
	v_cvt_pk_bf16_f32 v220, v74, v75
	v_cvt_pk_bf16_f32 v221, v76, v77
	v_cvt_pk_bf16_f32 v222, v78, v79
	v_cvt_pk_bf16_f32 v223, v80, v81
	v_add_f32_e32 v121, v121, v252
	v_add_f32_e32 v121, v121, v253
	s_waitcnt lgkmcnt(9)
	v_mfma_f32_32x32x16_bf16 v[66:81], v[232:235], v[110:113], 0
	ds_read_b128 v[232:235], v0 offset:512
	v_cvt_pk_bf16_f32 v224, v82, v83
	v_cvt_pk_bf16_f32 v225, v84, v85
	v_cvt_pk_bf16_f32 v226, v86, v87
	v_cvt_pk_bf16_f32 v227, v88, v89
	s_waitcnt lgkmcnt(9)
	v_mfma_f32_32x32x16_bf16 v[66:81], v[236:239], v[106:109], v[66:81]
	ds_read_b128 v[236:239], v0 offset:2560
	v_cvt_pk_bf16_f32 v228, v90, v91
	v_cvt_pk_bf16_f32 v229, v92, v93
	v_cvt_pk_bf16_f32 v230, v94, v95
	v_cvt_pk_bf16_f32 v231, v96, v97
	s_waitcnt lgkmcnt(9)
	v_mfma_f32_32x32x16_bf16 v[66:81], v[240:243], v[102:105], v[66:81]
	ds_read_b128 v[240:243], v0 offset:4608
	s_waitcnt lgkmcnt(9)
	v_mfma_f32_32x32x16_bf16 v[66:81], v[244:247], v[98:101], v[66:81]
	ds_read_b128 v[244:247], v0 offset:6656
	s_waitcnt lgkmcnt(3)
	v_mfma_f32_32x32x16_bf16 v[82:97], v[232:235], v[110:113], 0
	ds_read_b64_tr_b16 v[232:233], v125 offset:19456
	ds_read_b64_tr_b16 v[234:235], v125 offset:19968
	s_waitcnt lgkmcnt(4)
	v_mfma_f32_32x32x16_bf16 v[82:97], v[236:239], v[106:109], v[82:97]
	ds_read_b64_tr_b16 v[236:237], v125 offset:20480
	ds_read_b64_tr_b16 v[238:239], v125 offset:20992
	s_waitcnt lgkmcnt(5)
	v_mfma_f32_32x32x16_bf16 v[82:97], v[240:243], v[102:105], v[82:97]
	ds_read_b64_tr_b16 v[240:241], v125 offset:21504
	ds_read_b64_tr_b16 v[242:243], v125 offset:22016
	s_waitcnt lgkmcnt(6)
	v_mfma_f32_32x32x16_bf16 v[82:97], v[244:247], v[98:101], v[82:97]
	ds_read_b64_tr_b16 v[244:245], v125 offset:22528
	ds_read_b64_tr_b16 v[246:247], v125 offset:23040
	v_mfma_f32_32x32x16_bf16 v[50:65], v[216:219], v[248:251], v[50:65]
	ds_read_b64_tr_b16 v[248:249], v125 offset:23552
	ds_read_b64_tr_b16 v[250:251], v125 offset:24064
	v_exp_f32_e32 v66, v66
	v_exp_f32_e32 v67, v67
	v_mfma_f32_32x32x16_bf16 v[50:65], v[220:223], v[158:161], v[50:65]
	ds_read_b64_tr_b16 v[158:159], v125 offset:24576
	ds_read_b64_tr_b16 v[160:161], v125 offset:25088
	v_add_f32_e32 v252, v66, v67
	v_exp_f32_e32 v68, v68
	v_exp_f32_e32 v69, v69
	v_mfma_f32_32x32x16_bf16 v[50:65], v[224:227], v[166:169], v[50:65]
	ds_read_b64_tr_b16 v[166:167], v125 offset:25600
	ds_read_b64_tr_b16 v[168:169], v125 offset:26112
	v_add_f32_e32 v252, v252, v68
	v_add_f32_e32 v252, v252, v69
	v_exp_f32_e32 v70, v70
	v_exp_f32_e32 v71, v71
	s_waitcnt lgkmcnt(12)
	v_mfma_f32_32x32x16_bf16 v[50:65], v[228:231], v[232:235], v[50:65]
	ds_read_b64_tr_b16 v[232:233], v125 offset:26624
	ds_read_b64_tr_b16 v[234:235], v125 offset:27136
	v_add_f32_e32 v252, v252, v70
	v_add_f32_e32 v252, v252, v71
	v_exp_f32_e32 v72, v72
	v_exp_f32_e32 v73, v73
	s_waitcnt lgkmcnt(12)
	v_mfma_f32_32x32x16_bf16 v[34:49], v[216:219], v[236:239], v[34:49]
	ds_read_b64_tr_b16 v[236:237], v125 offset:27648
	ds_read_b64_tr_b16 v[238:239], v125 offset:28160
	v_add_f32_e32 v252, v252, v72
	v_add_f32_e32 v252, v252, v73
	v_exp_f32_e32 v74, v74
	v_exp_f32_e32 v75, v75
	s_waitcnt lgkmcnt(12)
	v_mfma_f32_32x32x16_bf16 v[34:49], v[220:223], v[240:243], v[34:49]
	ds_read_b64_tr_b16 v[240:241], v125 offset:28672
	ds_read_b64_tr_b16 v[242:243], v125 offset:29184
	v_add_f32_e32 v252, v252, v74
	v_add_f32_e32 v252, v252, v75
	v_exp_f32_e32 v76, v76
	v_exp_f32_e32 v77, v77
	s_waitcnt lgkmcnt(12)
	v_mfma_f32_32x32x16_bf16 v[34:49], v[224:227], v[244:247], v[34:49]
	ds_read_b64_tr_b16 v[244:245], v125 offset:29696
	ds_read_b64_tr_b16 v[246:247], v125 offset:30208
	v_add_f32_e32 v252, v252, v76
	v_add_f32_e32 v252, v252, v77
	v_exp_f32_e32 v78, v78
	v_exp_f32_e32 v79, v79
	s_waitcnt lgkmcnt(12)
	v_mfma_f32_32x32x16_bf16 v[34:49], v[228:231], v[248:251], v[34:49]
	ds_read_b64_tr_b16 v[248:249], v125 offset:30720
	ds_read_b64_tr_b16 v[250:251], v125 offset:31232
	v_add_f32_e32 v252, v252, v78
	v_add_f32_e32 v252, v252, v79
	v_exp_f32_e32 v80, v80
	v_exp_f32_e32 v81, v81
	s_waitcnt lgkmcnt(12)
	v_mfma_f32_32x32x16_bf16 v[18:33], v[216:219], v[158:161], v[18:33]
	ds_read_b64_tr_b16 v[158:159], v125 offset:31744
	ds_read_b64_tr_b16 v[160:161], v125 offset:32256
	v_add_f32_e32 v252, v252, v80
	v_add_f32_e32 v252, v252, v81
	v_exp_f32_e32 v82, v82
	v_exp_f32_e32 v83, v83
	s_waitcnt lgkmcnt(12)
	v_mfma_f32_32x32x16_bf16 v[18:33], v[220:223], v[166:169], v[18:33]
	v_add_f32_e32 v253, v82, v83
	v_exp_f32_e32 v84, v84
	v_exp_f32_e32 v85, v85
	s_waitcnt lgkmcnt(10)
	v_mfma_f32_32x32x16_bf16 v[18:33], v[224:227], v[232:235], v[18:33]
	v_add_f32_e32 v253, v253, v84
	v_add_f32_e32 v253, v253, v85
	v_exp_f32_e32 v86, v86
	v_exp_f32_e32 v87, v87
	s_waitcnt lgkmcnt(8)
	v_mfma_f32_32x32x16_bf16 v[18:33], v[228:231], v[236:239], v[18:33]
	v_add_f32_e32 v253, v253, v86
	v_add_f32_e32 v253, v253, v87
	v_exp_f32_e32 v88, v88
	v_exp_f32_e32 v89, v89
	s_waitcnt lgkmcnt(6)
	v_mfma_f32_32x32x16_bf16 v[2:17], v[216:219], v[240:243], v[2:17]
	v_add_f32_e32 v253, v253, v88
	v_add_f32_e32 v253, v253, v89
	v_exp_f32_e32 v90, v90
	v_exp_f32_e32 v91, v91
	s_waitcnt lgkmcnt(4)
	v_mfma_f32_32x32x16_bf16 v[2:17], v[220:223], v[244:247], v[2:17]
	v_add_f32_e32 v253, v253, v90
	v_add_f32_e32 v253, v253, v91
	v_exp_f32_e32 v92, v92
	v_exp_f32_e32 v93, v93
	s_waitcnt lgkmcnt(2)
	v_mfma_f32_32x32x16_bf16 v[2:17], v[224:227], v[248:251], v[2:17]
	v_add_f32_e32 v253, v253, v92
	v_add_f32_e32 v253, v253, v93
	v_exp_f32_e32 v94, v94
	v_exp_f32_e32 v95, v95
	s_waitcnt lgkmcnt(0)
	v_mfma_f32_32x32x16_bf16 v[2:17], v[228:231], v[158:161], v[2:17]
	v_add_f32_e32 v253, v253, v94
	v_add_f32_e32 v253, v253, v95
	v_exp_f32_e32 v96, v96
	v_exp_f32_e32 v97, v97
	v_add_f32_e32 v253, v253, v96
	v_add_f32_e32 v253, v253, v97
	s_add_i32 s16, s16, 1
	s_add_i32 s36, s40, 1
	s_cmp_lg_u32 s40, 2
	s_cselect_b32 s40, s36, 0
	s_waitcnt vmcnt(0)
	s_barrier
; __device__ __forceinline__ unsigned cvtpk_s(float lo, float hi) { f32x2_t v = {lo, hi}; bf16x2_t b = __builtin_convertvector(v, bf16x2_t); return __builtin_bit_cast(unsigned, b); }
; #define ATT_SBAR() __builtin_amdgcn_sched_barrier(0)
; #define ATT_VLOAD(dst, d0) do { _Pragma("unroll") for (int ks = 0; ks < 4; ++ks) { dst[2 * ks] = vtr(vp + (d0) * 4096 + ks * 1024); dst[2 * ks + 1] = vtr(vp + (d0) * 4096 + ks * 1024 + 512); } } while (0)
; #define ATT_PV(acc, src) do { _Pragma("unroll") for (int ks = 0; ks < 4; ++ks) { const bf16x8 vf_ = (bf16x8){src[2 * ks][0], src[2 * ks][1], src[2 * ks][2], src[2 * ks][3], src[2 * ks + 1][0], src[2 * ks + 1][1], src[2 * ks + 1][2], src[2 * ks + 1][3]}; \
;                 acc = __builtin_amdgcn_mfma_f32_32x32x16_bf16(__builtin_bit_cast(bf16x8, pw[ks]), vf_, acc, 0, 0, 0); } } while (0)
; __device__ __forceinline__ void attn_unit(const int b, const int h, const int qb, const bf16_t* Q, const bf16_t* K, const bf16_t* V, bf16_t* O, ATT_LAS char* shm, const float lam) {
;     ...
;             for (int r = 0; r < 16; ++r) { p0[r] = __builtin_amdgcn_exp2f(p0[r]); p1[r] = __builtin_amdgcn_exp2f(p1[r]); }
;             u32x4 pw[4];
; #pragma unroll
;             for (int j = 0; j < 4; ++j) { pw[0][j] = cvtpk_s(p0[2 * j], p0[2 * j + 1]); pw[1][j] = cvtpk_s(p0[8 + 2 * j], p0[9 + 2 * j]); pw[2][j] = cvtpk_s(p1[2 * j], p1[2 * j + 1]); pw[3][j] = cvtpk_s(p1[8 + 2 * j], p1[9 + 2 * j]); }
;             { float sa = 0.f, sb = 0.f;
; #pragma unroll
;               for (int r = 0; r < 16; ++r) { sa += p0[r]; sb += p1[r]; }
;               l_reg += sa + sb; }
;             ATT_PV(o[0], va);
;             ATT_SBAR();
;             ATT_VLOAD(va, 2);
;             ATT_SBAR();
;             ATT_PV(o[1], vb);
;             ATT_SBAR();
;             ATT_VLOAD(vb, 3);
;             ATT_SBAR();
;             ATT_PV(o[2], va);
;             ATT_SBAR();
;             ATT_PV(o[3], vb);
	s_lshl_b32 s37, s40, 15
	v_add_u32_e32 v125, s37, v156
	ds_read_b64_tr_b16 v[248:249], v125 offset:16384
	ds_read_b64_tr_b16 v[250:251], v125 offset:16896
	ds_read_b64_tr_b16 v[158:159], v125 offset:17408
	ds_read_b64_tr_b16 v[160:161], v125 offset:17920
	ds_read_b64_tr_b16 v[166:167], v125 offset:18432
	ds_read_b64_tr_b16 v[168:169], v125 offset:18944
	ds_read_b64_tr_b16 v[232:233], v125 offset:19456
	ds_read_b64_tr_b16 v[234:235], v125 offset:19968
	ds_read_b64_tr_b16 v[236:237], v125 offset:20480
	ds_read_b64_tr_b16 v[238:239], v125 offset:20992
	ds_read_b64_tr_b16 v[240:241], v125 offset:21504
	ds_read_b64_tr_b16 v[242:243], v125 offset:22016
	ds_read_b64_tr_b16 v[244:245], v125 offset:22528
	ds_read_b64_tr_b16 v[246:247], v125 offset:23040
	v_cvt_pk_bf16_f32 v216, v66, v67
	v_cvt_pk_bf16_f32 v217, v68, v69
	v_cvt_pk_bf16_f32 v218, v70, v71
	v_cvt_pk_bf16_f32 v219, v72, v73
	v_cvt_pk_bf16_f32 v220, v74, v75
	v_cvt_pk_bf16_f32 v221, v76, v77
	v_cvt_pk_bf16_f32 v222, v78, v79
	v_cvt_pk_bf16_f32 v223, v80, v81
	v_cvt_pk_bf16_f32 v224, v82, v83
	v_cvt_pk_bf16_f32 v225, v84, v85
	v_cvt_pk_bf16_f32 v226, v86, v87
	v_cvt_pk_bf16_f32 v227, v88, v89
	v_cvt_pk_bf16_f32 v228, v90, v91
	v_cvt_pk_bf16_f32 v229, v92, v93
	v_cvt_pk_bf16_f32 v230, v94, v95
	v_cvt_pk_bf16_f32 v231, v96, v97
	v_add_f32_e32 v121, v121, v252
	v_add_f32_e32 v121, v121, v253
	s_waitcnt lgkmcnt(12)
	v_mfma_f32_32x32x16_bf16 v[50:65], v[216:219], v[248:251], v[50:65]
	ds_read_b64_tr_b16 v[248:249], v125 offset:23552
	ds_read_b64_tr_b16 v[250:251], v125 offset:24064
	s_waitcnt lgkmcnt(12)
	v_mfma_f32_32x32x16_bf16 v[50:65], v[220:223], v[158:161], v[50:65]
	ds_read_b64_tr_b16 v[158:159], v125 offset:24576
	ds_read_b64_tr_b16 v[160:161], v125 offset:25088
	s_waitcnt lgkmcnt(12)
	v_mfma_f32_32x32x16_bf16 v[50:65], v[224:227], v[166:169], v[50:65]
	ds_read_b64_tr_b16 v[166:167], v125 offset:25600
	ds_read_b64_tr_b16 v[168:169], v125 offset:26112
	s_waitcnt lgkmcnt(12)
	v_mfma_f32_32x32x16_bf16 v[50:65], v[228:231], v[232:235], v[50:65]
	ds_read_b64_tr_b16 v[232:233], v125 offset:26624
	ds_read_b64_tr_b16 v[234:235], v125 offset:27136
	s_waitcnt lgkmcnt(12)
	v_mfma_f32_32x32x16_bf16 v[34:49], v[216:219], v[236:239], v[34:49]
	ds_read_b64_tr_b16 v[236:237], v125 offset:27648
	ds_read_b64_tr_b16 v[238:239], v125 offset:28160
	s_waitcnt lgkmcnt(12)
	v_mfma_f32_32x32x16_bf16 v[34:49], v[220:223], v[240:243], v[34:49]
	ds_read_b64_tr_b16 v[240:241], v125 offset:28672
	ds_read_b64_tr_b16 v[242:243], v125 offset:29184
	s_waitcnt lgkmcnt(12)
	v_mfma_f32_32x32x16_bf16 v[34:49], v[224:227], v[244:247], v[34:49]
	ds_read_b64_tr_b16 v[244:245], v125 offset:29696
	ds_read_b64_tr_b16 v[246:247], v125 offset:30208
	s_waitcnt lgkmcnt(12)
	v_mfma_f32_32x32x16_bf16 v[34:49], v[228:231], v[248:251], v[34:49]
	ds_read_b64_tr_b16 v[248:249], v125 offset:30720
	ds_read_b64_tr_b16 v[250:251], v125 offset:31232
	s_waitcnt lgkmcnt(12)
	v_mfma_f32_32x32x16_bf16 v[18:33], v[216:219], v[158:161], v[18:33]
	ds_read_b64_tr_b16 v[158:159], v125 offset:31744
	ds_read_b64_tr_b16 v[160:161], v125 offset:32256
	s_waitcnt lgkmcnt(12)
	v_mfma_f32_32x32x16_bf16 v[18:33], v[220:223], v[166:169], v[18:33]
	s_waitcnt lgkmcnt(10)
	v_mfma_f32_32x32x16_bf16 v[18:33], v[224:227], v[232:235], v[18:33]
	s_waitcnt lgkmcnt(8)
	v_mfma_f32_32x32x16_bf16 v[18:33], v[228:231], v[236:239], v[18:33]
	s_waitcnt lgkmcnt(6)
	v_mfma_f32_32x32x16_bf16 v[2:17], v[216:219], v[240:243], v[2:17]
	s_waitcnt lgkmcnt(4)
	v_mfma_f32_32x32x16_bf16 v[2:17], v[220:223], v[244:247], v[2:17]
	s_waitcnt lgkmcnt(2)
	v_mfma_f32_32x32x16_bf16 v[2:17], v[224:227], v[248:251], v[2:17]
	s_waitcnt lgkmcnt(0)
	v_mfma_f32_32x32x16_bf16 v[2:17], v[228:231], v[158:161], v[2:17]
	s_branch .LBB0_474
; __device__ __forceinline__ unsigned cvtpk_s(float lo, float hi) { f32x2_t v = {lo, hi}; bf16x2_t b = __builtin_convertvector(v, bf16x2_t); return __builtin_bit_cast(unsigned, b); }
; #define ATT_SBAR() __builtin_amdgcn_sched_barrier(0)
; #define ATT_VLOAD(dst, d0) do { _Pragma("unroll") for (int ks = 0; ks < 4; ++ks) { dst[2 * ks] = vtr(vp + (d0) * 4096 + ks * 1024); dst[2 * ks + 1] = vtr(vp + (d0) * 4096 + ks * 1024 + 512); } } while (0)
; #define ATT_PV(acc, src) do { _Pragma("unroll") for (int ks = 0; ks < 4; ++ks) { const bf16x8 vf_ = (bf16x8){src[2 * ks][0], src[2 * ks][1], src[2 * ks][2], src[2 * ks][3], src[2 * ks + 1][0], src[2 * ks + 1][1], src[2 * ks + 1][2], src[2 * ks + 1][3]}; \
;                 acc = __builtin_amdgcn_mfma_f32_32x32x16_bf16(__builtin_bit_cast(bf16x8, pw[ks]), vf_, acc, 0, 0, 0); } } while (0)
; __device__ __forceinline__ void attn_unit(const int b, const int h, const int qb, const bf16_t* Q, const bf16_t* K, const bf16_t* V, bf16_t* O, ATT_LAS char* shm, const float lam) {
;     ...
;             for (int r = 0; r < 16; ++r) { p0[r] = __builtin_amdgcn_exp2f(p0[r]); p1[r] = __builtin_amdgcn_exp2f(p1[r]); }
;             u32x4 pw[4];
; #pragma unroll
;             for (int j = 0; j < 4; ++j) { pw[0][j] = cvtpk_s(p0[2 * j], p0[2 * j + 1]); pw[1][j] = cvtpk_s(p0[8 + 2 * j], p0[9 + 2 * j]); pw[2][j] = cvtpk_s(p1[2 * j], p1[2 * j + 1]); pw[3][j] = cvtpk_s(p1[8 + 2 * j], p1[9 + 2 * j]); }
;             { float sa = 0.f, sb = 0.f;
; #pragma unroll
;               for (int r = 0; r < 16; ++r) { sa += p0[r]; sb += p1[r]; }
;               l_reg += sa + sb; }
;             ATT_PV(o[0], va);
;             ATT_SBAR();
;             ATT_VLOAD(va, 2);
;             ATT_SBAR();
;             ATT_PV(o[1], vb);
;             ATT_SBAR();
;             ATT_VLOAD(vb, 3);
;             ATT_SBAR();
;             ATT_PV(o[2], va);
;             ATT_SBAR();
;             ATT_PV(o[3], vb);
.Latt_low:
	s_lshl_b32 s37, s40, 15
	v_add_u32_e32 v125, s37, v156
	ds_read_b64_tr_b16 v[248:249], v125 offset:16384
	ds_read_b64_tr_b16 v[250:251], v125 offset:16896
	ds_read_b64_tr_b16 v[158:159], v125 offset:17408
	ds_read_b64_tr_b16 v[160:161], v125 offset:17920
	ds_read_b64_tr_b16 v[166:167], v125 offset:18432
	ds_read_b64_tr_b16 v[168:169], v125 offset:18944
	ds_read_b64_tr_b16 v[232:233], v125 offset:19456
	ds_read_b64_tr_b16 v[234:235], v125 offset:19968
	ds_read_b64_tr_b16 v[236:237], v125 offset:20480
	ds_read_b64_tr_b16 v[238:239], v125 offset:20992
	ds_read_b64_tr_b16 v[240:241], v125 offset:21504
	ds_read_b64_tr_b16 v[242:243], v125 offset:22016
	ds_read_b64_tr_b16 v[244:245], v125 offset:22528
	ds_read_b64_tr_b16 v[246:247], v125 offset:23040
	v_cvt_pk_bf16_f32 v216, v66, v67
	v_cvt_pk_bf16_f32 v217, v68, v69
	v_cvt_pk_bf16_f32 v218, v70, v71
	v_cvt_pk_bf16_f32 v219, v72, v73
	v_cvt_pk_bf16_f32 v220, v74, v75
	v_cvt_pk_bf16_f32 v221, v76, v77
	v_cvt_pk_bf16_f32 v222, v78, v79
	v_cvt_pk_bf16_f32 v223, v80, v81
	v_cvt_pk_bf16_f32 v224, v82, v83
	v_cvt_pk_bf16_f32 v225, v84, v85
	v_cvt_pk_bf16_f32 v226, v86, v87
	v_cvt_pk_bf16_f32 v227, v88, v89
	v_cvt_pk_bf16_f32 v228, v90, v91
	v_cvt_pk_bf16_f32 v229, v92, v93
	v_cvt_pk_bf16_f32 v230, v94, v95
	v_cvt_pk_bf16_f32 v231, v96, v97
	v_add_f32_e32 v121, v121, v252
	v_add_f32_e32 v121, v121, v253
	s_waitcnt lgkmcnt(12)
	v_mfma_f32_32x32x16_bf16 v[50:65], v[216:219], v[248:251], v[50:65]
	ds_read_b64_tr_b16 v[248:249], v125 offset:23552
	ds_read_b64_tr_b16 v[250:251], v125 offset:24064
	s_waitcnt lgkmcnt(12)
	v_mfma_f32_32x32x16_bf16 v[50:65], v[220:223], v[158:161], v[50:65]
	ds_read_b64_tr_b16 v[158:159], v125 offset:24576
	ds_read_b64_tr_b16 v[160:161], v125 offset:25088
	s_waitcnt lgkmcnt(12)
	v_mfma_f32_32x32x16_bf16 v[50:65], v[224:227], v[166:169], v[50:65]
	ds_read_b64_tr_b16 v[166:167], v125 offset:25600
	ds_read_b64_tr_b16 v[168:169], v125 offset:26112
	s_waitcnt lgkmcnt(12)
	v_mfma_f32_32x32x16_bf16 v[50:65], v[228:231], v[232:235], v[50:65]
	ds_read_b64_tr_b16 v[232:233], v125 offset:26624
	ds_read_b64_tr_b16 v[234:235], v125 offset:27136
	s_waitcnt lgkmcnt(12)
	v_mfma_f32_32x32x16_bf16 v[34:49], v[216:219], v[236:239], v[34:49]
	ds_read_b64_tr_b16 v[236:237], v125 offset:27648
	ds_read_b64_tr_b16 v[238:239], v125 offset:28160
	s_waitcnt lgkmcnt(12)
	v_mfma_f32_32x32x16_bf16 v[34:49], v[220:223], v[240:243], v[34:49]
	ds_read_b64_tr_b16 v[240:241], v125 offset:28672
	ds_read_b64_tr_b16 v[242:243], v125 offset:29184
	s_waitcnt lgkmcnt(12)
	v_mfma_f32_32x32x16_bf16 v[34:49], v[224:227], v[244:247], v[34:49]
	ds_read_b64_tr_b16 v[244:245], v125 offset:29696
	ds_read_b64_tr_b16 v[246:247], v125 offset:30208
	s_waitcnt lgkmcnt(12)
	v_mfma_f32_32x32x16_bf16 v[34:49], v[228:231], v[248:251], v[34:49]
	ds_read_b64_tr_b16 v[248:249], v125 offset:30720
	ds_read_b64_tr_b16 v[250:251], v125 offset:31232
	s_waitcnt lgkmcnt(12)
	v_mfma_f32_32x32x16_bf16 v[18:33], v[216:219], v[158:161], v[18:33]
	ds_read_b64_tr_b16 v[158:159], v125 offset:31744
	ds_read_b64_tr_b16 v[160:161], v125 offset:32256
	s_waitcnt lgkmcnt(12)
	v_mfma_f32_32x32x16_bf16 v[18:33], v[220:223], v[166:169], v[18:33]
	s_waitcnt lgkmcnt(10)
	v_mfma_f32_32x32x16_bf16 v[18:33], v[224:227], v[232:235], v[18:33]
	s_waitcnt lgkmcnt(8)
	v_mfma_f32_32x32x16_bf16 v[18:33], v[228:231], v[236:239], v[18:33]
	s_waitcnt lgkmcnt(6)
	v_mfma_f32_32x32x16_bf16 v[2:17], v[216:219], v[240:243], v[2:17]
	s_waitcnt lgkmcnt(4)
	v_mfma_f32_32x32x16_bf16 v[2:17], v[220:223], v[244:247], v[2:17]
	s_waitcnt lgkmcnt(2)
	v_mfma_f32_32x32x16_bf16 v[2:17], v[224:227], v[248:251], v[2:17]
	s_waitcnt lgkmcnt(0)
	v_mfma_f32_32x32x16_bf16 v[2:17], v[228:231], v[158:161], v[2:17]
	s_waitcnt vmcnt(0)
	s_barrier

; __global__ void __launch_bounds__(NWAVES * 64, 2) hybrid_fwd(Args args) {
	.amdhsa_kernel _Z10hybrid_fwd4Args
		.amdhsa_group_segment_fixed_size 0
		.amdhsa_private_segment_fixed_size 0
		.amdhsa_kernarg_size 424
		.amdhsa_user_sgpr_count 2
		.amdhsa_user_sgpr_dispatch_ptr 0
		.amdhsa_user_sgpr_queue_ptr 0
		.amdhsa_user_sgpr_kernarg_segment_ptr 1
		.amdhsa_user_sgpr_dispatch_id 0
		.amdhsa_user_sgpr_kernarg_preload_length 0
		.amdhsa_user_sgpr_kernarg_preload_offset 0
		.amdhsa_user_sgpr_private_segment_size 0
		.amdhsa_uses_dynamic_stack 0
		.amdhsa_enable_private_segment 0
		.amdhsa_system_sgpr_workgroup_id_x 1
		.amdhsa_system_sgpr_workgroup_id_y 0
		.amdhsa_system_sgpr_workgroup_id_z 0
		.amdhsa_system_sgpr_workgroup_info 0
		.amdhsa_system_vgpr_workitem_id 2
		.amdhsa_next_free_vgpr 256
		.amdhsa_next_free_sgpr 100
		.amdhsa_accum_offset 256
		.amdhsa_reserve_vcc 1
		.amdhsa_float_round_mode_32 0
		.amdhsa_float_round_mode_16_64 0
		.amdhsa_float_denorm_mode_32 3
		.amdhsa_float_denorm_mode_16_64 3
		.amdhsa_dx10_clamp 1
		.amdhsa_ieee_mode 1
		.amdhsa_fp16_overflow 0
		.amdhsa_tg_split 0
		.amdhsa_exception_fp_ieee_invalid_op 0
		.amdhsa_exception_fp_denorm_src 0
		.amdhsa_exception_fp_ieee_div_zero 0
		.amdhsa_exception_fp_ieee_overflow 0
		.amdhsa_exception_fp_ieee_underflow 0
		.amdhsa_exception_fp_ieee_inexact 0
		.amdhsa_exception_int_div_zero 0
	.end_amdhsa_kernel

; __global__ void __launch_bounds__(NWAVES * 64, 2) hybrid_fwd(Args args) {
amdhsa.kernels:
  - .agpr_count:     0
    .args:
      - .offset:         0
        .size:           168
        .value_kind:     by_value
      - .offset:         168
        .size:           4
        .value_kind:     hidden_block_count_x
      - .offset:         172
        .size:           4
        .value_kind:     hidden_block_count_y
      - .offset:         176
        .size:           4
        .value_kind:     hidden_block_count_z
      - .offset:         180
        .size:           2
        .value_kind:     hidden_group_size_x
      - .offset:         182
        .size:           2
        .value_kind:     hidden_group_size_y
      - .offset:         184
        .size:           2
        .value_kind:     hidden_group_size_z
      - .offset:         186
        .size:           2
        .value_kind:     hidden_remainder_x
      - .offset:         188
        .size:           2
        .value_kind:     hidden_remainder_y
      - .offset:         190
        .size:           2
        .value_kind:     hidden_remainder_z
      - .offset:         208
        .size:           8
        .value_kind:     hidden_global_offset_x
      - .offset:         216
        .size:           8
        .value_kind:     hidden_global_offset_y
      - .offset:         224
        .size:           8
        .value_kind:     hidden_global_offset_z
      - .offset:         232
        .size:           2
        .value_kind:     hidden_grid_dims
      - .offset:         256
        .size:           8
        .value_kind:     hidden_multigrid_sync_arg
      - .offset:         288
        .size:           4
        .value_kind:     hidden_dynamic_lds_size
    .group_segment_fixed_size: 0
    .kernarg_segment_align: 8
    .kernarg_segment_size: 424
    .language:       OpenCL C
    .language_version:
      - 2
      - 0
    .max_flat_workgroup_size: 512
    .name:           _Z10hybrid_fwd4Args
    .private_segment_fixed_size: 0
    .sgpr_count:     106
    .sgpr_spill_count: 13
    .symbol:         _Z10hybrid_fwd4Args.kd
    .uniform_work_group_size: 1
    .uses_dynamic_stack: false
    .vgpr_count:     256
    .vgpr_spill_count: 0
    .wavefront_size: 64
